# attention loop: QK K-fragment reads all issued up front, PV V-fragment reads 4 deep (4 buffers), counted lgkmcnt
# speedup vs baseline: 1.0295x; 1.0067x over previous
.LBB0_203:
	v_sub_f32_e32 v103, v103, v234
	v_sub_f32_e32 v102, v102, v234
	v_sub_f32_e32 v101, v101, v234
	v_sub_f32_e32 v100, v100, v234
	v_sub_f32_e32 v99, v99, v234
	v_sub_f32_e32 v98, v98, v234
	v_sub_f32_e32 v97, v97, v234
	v_sub_f32_e32 v96, v96, v234
	v_sub_f32_e32 v119, v119, v234
	v_sub_f32_e32 v118, v118, v234
	v_sub_f32_e32 v117, v117, v234
	v_sub_f32_e32 v116, v116, v234
	v_sub_f32_e32 v115, v115, v234
	v_sub_f32_e32 v114, v114, v234
	v_sub_f32_e32 v113, v113, v234
	v_sub_f32_e32 v112, v112, v234
	v_sub_f32_e32 v107, v107, v234
	v_sub_f32_e32 v106, v106, v234
	v_sub_f32_e32 v105, v105, v234
	v_sub_f32_e32 v104, v104, v234
	v_sub_f32_e32 v123, v123, v234
	v_sub_f32_e32 v122, v122, v234
	v_sub_f32_e32 v121, v121, v234
	v_sub_f32_e32 v120, v120, v234
	v_exp_f32_e32 v96, v96
	v_exp_f32_e32 v97, v97
	v_exp_f32_e32 v98, v98
	v_exp_f32_e32 v99, v99
	v_exp_f32_e32 v100, v100
	v_exp_f32_e32 v101, v101
	v_exp_f32_e32 v102, v102
	v_exp_f32_e32 v103, v103
	v_exp_f32_e32 v112, v112
	v_exp_f32_e32 v113, v113
	v_exp_f32_e32 v114, v114
	v_exp_f32_e32 v115, v115
	v_exp_f32_e32 v116, v116
	v_exp_f32_e32 v117, v117
	v_exp_f32_e32 v118, v118
	v_exp_f32_e32 v119, v119
	v_sub_f32_e32 v111, v111, v234
	v_sub_f32_e32 v110, v110, v234
	v_sub_f32_e32 v109, v109, v234
	v_sub_f32_e32 v108, v108, v234
	v_sub_f32_e32 v127, v127, v234
	v_sub_f32_e32 v126, v126, v234
	v_sub_f32_e32 v125, v125, v234
	v_sub_f32_e32 v124, v124, v234
	v_exp_f32_e32 v104, v104
	v_exp_f32_e32 v105, v105
	v_exp_f32_e32 v106, v106
	v_exp_f32_e32 v107, v107
	v_exp_f32_e32 v120, v120
	v_exp_f32_e32 v122, v122
	v_exp_f32_e32 v123, v123
	v_exp_f32_e32 v121, v121
	v_exp_f32_e32 v108, v108
	v_exp_f32_e32 v109, v109
	v_exp_f32_e32 v110, v110
	v_exp_f32_e32 v111, v111
	v_exp_f32_e32 v124, v124
	v_exp_f32_e32 v125, v125
	v_exp_f32_e32 v126, v126
	v_exp_f32_e32 v127, v127
	v_pk_add_f32 v[226:227], v[100:101], v[116:117]
	v_pk_add_f32 v[236:237], v[96:97], v[112:113]
	v_pk_add_f32 v[238:239], v[102:103], v[118:119]
	v_pk_add_f32 v[240:241], v[98:99], v[114:115]
	v_pk_add_f32 v[222:223], v[106:107], v[122:123]
	v_pk_add_f32 v[224:225], v[104:105], v[120:121]
	v_pk_add_f32 v[238:239], v[240:241], v[238:239]
	v_pk_add_f32 v[226:227], v[236:237], v[226:227]
	v_pk_add_f32 v[162:163], v[108:109], v[124:125]
	v_pk_add_f32 v[164:165], v[110:111], v[126:127]
	v_pk_add_f32 v[224:225], v[224:225], v[226:227]
	v_pk_add_f32 v[222:223], v[222:223], v[238:239]
	v_pk_add_f32 v[162:163], v[162:163], v[224:225]
	v_pk_add_f32 v[164:165], v[164:165], v[222:223]
	v_add_f32_e32 v162, v162, v163
	v_add_f32_e32 v163, v164, v165
	v_add_f32_e32 v162, v162, v163
	v_fmac_f32_e32 v162, v215, v170
	s_setprio 1
	ds_read_b128 v[222:225], v209
	ds_read_b128 v[240:243], v209 offset:4608
	ds_read_b128 v[244:247], v209 offset:9216
	ds_read_b128 v[248:251], v209 offset:13824
	v_cvt_pk_bf16_f32 v236, v96, v97
	v_cvt_pk_bf16_f32 v237, v98, v99
	v_cvt_pk_bf16_f32 v238, v100, v101
	v_cvt_pk_bf16_f32 v239, v102, v103
	s_waitcnt lgkmcnt(3)
	s_nop 0
	v_mfma_f32_32x32x16_bf16 v[48:63], v[222:225], v[236:239], v[48:63]
	ds_read_b128 v[222:225], v209 offset:32
	s_waitcnt lgkmcnt(3)
	v_mfma_f32_32x32x16_bf16 v[32:47], v[240:243], v[236:239], v[32:47]
	ds_read_b128 v[240:243], v209 offset:4640
	s_waitcnt lgkmcnt(3)
	v_mfma_f32_32x32x16_bf16 v[16:31], v[244:247], v[236:239], v[16:31]
	ds_read_b128 v[244:247], v209 offset:9248
	s_waitcnt lgkmcnt(3)
	v_mfma_f32_32x32x16_bf16 v[0:15], v[248:251], v[236:239], v[0:15]
	ds_read_b128 v[248:251], v209 offset:13856
	v_cvt_pk_bf16_f32 v236, v104, v105
	v_cvt_pk_bf16_f32 v237, v106, v107
	v_cvt_pk_bf16_f32 v238, v108, v109
	v_cvt_pk_bf16_f32 v239, v110, v111
	s_waitcnt lgkmcnt(3)
	s_nop 0
	v_mfma_f32_32x32x16_bf16 v[48:63], v[222:225], v[236:239], v[48:63]
	ds_read_b128 v[222:225], v209 offset:64
	s_waitcnt lgkmcnt(3)
	v_mfma_f32_32x32x16_bf16 v[32:47], v[240:243], v[236:239], v[32:47]
	ds_read_b128 v[240:243], v209 offset:4672
	s_waitcnt lgkmcnt(3)
	v_mfma_f32_32x32x16_bf16 v[16:31], v[244:247], v[236:239], v[16:31]
	ds_read_b128 v[244:247], v209 offset:9280
	s_waitcnt lgkmcnt(3)
	v_mfma_f32_32x32x16_bf16 v[0:15], v[248:251], v[236:239], v[0:15]
	ds_read_b128 v[248:251], v209 offset:13888
	v_cvt_pk_bf16_f32 v236, v112, v113
	v_cvt_pk_bf16_f32 v237, v114, v115
	v_cvt_pk_bf16_f32 v238, v116, v117
	v_cvt_pk_bf16_f32 v239, v118, v119
	s_waitcnt lgkmcnt(3)
	s_nop 0
	v_mfma_f32_32x32x16_bf16 v[48:63], v[222:225], v[236:239], v[48:63]
	ds_read_b128 v[222:225], v209 offset:96
	s_waitcnt lgkmcnt(3)
	v_mfma_f32_32x32x16_bf16 v[32:47], v[240:243], v[236:239], v[32:47]
	ds_read_b128 v[240:243], v209 offset:4704
	s_waitcnt lgkmcnt(3)
	v_mfma_f32_32x32x16_bf16 v[16:31], v[244:247], v[236:239], v[16:31]
	ds_read_b128 v[244:247], v209 offset:9312
	s_waitcnt lgkmcnt(3)
	v_mfma_f32_32x32x16_bf16 v[0:15], v[248:251], v[236:239], v[0:15]
	ds_read_b128 v[248:251], v209 offset:13920
	v_cvt_pk_bf16_f32 v236, v120, v121
	v_cvt_pk_bf16_f32 v237, v122, v123
	v_cvt_pk_bf16_f32 v238, v124, v125
	v_cvt_pk_bf16_f32 v239, v126, v127
	s_waitcnt lgkmcnt(3)
	s_nop 0
	v_mfma_f32_32x32x16_bf16 v[48:63], v[222:225], v[236:239], v[48:63]
	s_waitcnt lgkmcnt(2)
	v_mfma_f32_32x32x16_bf16 v[32:47], v[240:243], v[236:239], v[32:47]
	s_waitcnt lgkmcnt(1)
	v_mfma_f32_32x32x16_bf16 v[16:31], v[244:247], v[236:239], v[16:31]
	s_waitcnt lgkmcnt(0)
	v_mfma_f32_32x32x16_bf16 v[0:15], v[248:251], v[236:239], v[0:15]
	s_setprio 0
	v_mov_b32_e32 v170, v234
	v_mov_b32_e32 v215, v162

.LBB0_205:
	s_add_i32 s17, s15, -1
	s_cmp_lt_u32 s17, s12
	s_cselect_b64 s[6:7], -1, 0
	s_and_b64 s[8:9], s[6:7], exec
	s_cselect_b32 s4, s17, s14
	s_lshl_b32 s4, s4, 6
	s_add_i32 s18, s15, -2
	s_or_b32 s19, s4, 32
	s_cmp_lt_u32 s18, s12
	s_cselect_b64 s[8:9], -1, 0
	v_mad_u64_u32 v[144:145], s[10:11], s4, v228, v[194:195]
	v_mad_u64_u32 v[148:149], s[10:11], s19, v228, v[194:195]
	s_and_b64 s[10:11], s[8:9], exec
	s_cselect_b32 s10, s18, s14
	s_lshl_b32 s10, s10, 6
	s_mov_b32 s11, s5
	v_lshl_add_u64 v[152:153], s[10:11], 1, v[196:197]
	v_add_co_u32_e32 v154, vcc, 0x80000, v152
	global_load_dwordx4 v[144:147], v[144:145], off
	s_nop 0
	global_load_dwordx4 v[148:151], v[148:149], off
	v_addc_co_u32_e32 v155, vcc, 0, v153, vcc
	global_load_dwordx4 v[156:159], v[152:153], off
	s_nop 0
	global_load_dwordx4 v[152:155], v[154:155], off
	s_sub_i32 s10, s13, 30
	v_cmp_le_u32_e32 vcc, s10, v212
	s_and_b64 s[10:11], s[8:9], vcc
	s_and_saveexec_b64 s[8:9], s[10:11]
	s_cbranch_execz .LBB0_207
	s_mul_i32 s10, s24, 0x4400
	s_setprio 1
	v_add3_u32 v162, v203, s10, v204
	ds_read_b128 v[112:115], v162
	ds_read_b128 v[116:119], v162 offset:32
	ds_read_b128 v[120:123], v162 offset:64
	ds_read_b128 v[124:127], v162 offset:96
	ds_read_b128 v[222:225], v162 offset:8704
	ds_read_b128 v[236:239], v162 offset:8736
	ds_read_b128 v[240:243], v162 offset:8768
	ds_read_b128 v[244:247], v162 offset:8800
	s_waitcnt lgkmcnt(7)
	v_mfma_f32_32x32x16_bf16 v[96:111], v[112:115], v[128:131], 0
	s_waitcnt lgkmcnt(6)
	v_mfma_f32_32x32x16_bf16 v[96:111], v[116:119], v[132:135], v[96:111]
	s_waitcnt lgkmcnt(5)
	v_mfma_f32_32x32x16_bf16 v[96:111], v[120:123], v[136:139], v[96:111]
	s_waitcnt lgkmcnt(4)
	v_mfma_f32_32x32x16_bf16 v[96:111], v[124:127], v[140:143], v[96:111]
	s_waitcnt lgkmcnt(3)
	v_mfma_f32_32x32x16_bf16 v[112:127], v[222:225], v[128:131], 0
	s_waitcnt lgkmcnt(2)
	v_mfma_f32_32x32x16_bf16 v[112:127], v[236:239], v[132:135], v[112:127]
	s_waitcnt lgkmcnt(1)
	v_mfma_f32_32x32x16_bf16 v[112:127], v[240:243], v[136:139], v[112:127]
	s_waitcnt lgkmcnt(0)
	v_mfma_f32_32x32x16_bf16 v[112:127], v[244:247], v[140:143], v[112:127]
	s_setprio 0

.LBB0_212:
	v_sub_f32_e32 v71, v71, v234
	v_sub_f32_e32 v70, v70, v234
	v_sub_f32_e32 v69, v69, v234
	v_sub_f32_e32 v68, v68, v234
	v_sub_f32_e32 v67, v67, v234
	v_sub_f32_e32 v66, v66, v234
	v_sub_f32_e32 v65, v65, v234
	v_sub_f32_e32 v64, v64, v234
	v_sub_f32_e32 v87, v87, v234
	v_sub_f32_e32 v86, v86, v234
	v_sub_f32_e32 v85, v85, v234
	v_sub_f32_e32 v84, v84, v234
	v_sub_f32_e32 v83, v83, v234
	v_sub_f32_e32 v82, v82, v234
	v_sub_f32_e32 v81, v81, v234
	v_sub_f32_e32 v80, v80, v234
	v_sub_f32_e32 v75, v75, v234
	v_sub_f32_e32 v74, v74, v234
	v_sub_f32_e32 v73, v73, v234
	v_sub_f32_e32 v72, v72, v234
	v_sub_f32_e32 v91, v91, v234
	v_sub_f32_e32 v90, v90, v234
	v_sub_f32_e32 v89, v89, v234
	v_sub_f32_e32 v88, v88, v234
	v_exp_f32_e32 v64, v64
	v_exp_f32_e32 v65, v65
	v_exp_f32_e32 v66, v66
	v_exp_f32_e32 v67, v67
	v_exp_f32_e32 v68, v68
	v_exp_f32_e32 v69, v69
	v_exp_f32_e32 v70, v70
	v_exp_f32_e32 v71, v71
	v_exp_f32_e32 v80, v80
	v_exp_f32_e32 v81, v81
	v_exp_f32_e32 v82, v82
	v_exp_f32_e32 v83, v83
	v_exp_f32_e32 v84, v84
	v_exp_f32_e32 v85, v85
	v_exp_f32_e32 v86, v86
	v_exp_f32_e32 v87, v87
	v_sub_f32_e32 v79, v79, v234
	v_sub_f32_e32 v78, v78, v234
	v_sub_f32_e32 v77, v77, v234
	v_sub_f32_e32 v76, v76, v234
	v_sub_f32_e32 v95, v95, v234
	v_sub_f32_e32 v94, v94, v234
	v_sub_f32_e32 v93, v93, v234
	v_sub_f32_e32 v92, v92, v234
	v_exp_f32_e32 v72, v72
	v_exp_f32_e32 v73, v73
	v_exp_f32_e32 v74, v74
	v_exp_f32_e32 v75, v75
	v_exp_f32_e32 v88, v88
	v_exp_f32_e32 v90, v90
	v_exp_f32_e32 v91, v91
	v_exp_f32_e32 v89, v89
	v_exp_f32_e32 v76, v76
	v_exp_f32_e32 v77, v77
	v_exp_f32_e32 v78, v78
	v_exp_f32_e32 v79, v79
	v_exp_f32_e32 v92, v92
	v_exp_f32_e32 v93, v93
	v_exp_f32_e32 v94, v94
	v_exp_f32_e32 v95, v95
	v_pk_add_f32 v[226:227], v[68:69], v[84:85]
	v_pk_add_f32 v[236:237], v[64:65], v[80:81]
	v_pk_add_f32 v[238:239], v[70:71], v[86:87]
	v_pk_add_f32 v[240:241], v[66:67], v[82:83]
	v_pk_add_f32 v[222:223], v[74:75], v[90:91]
	v_pk_add_f32 v[224:225], v[72:73], v[88:89]
	v_pk_add_f32 v[238:239], v[240:241], v[238:239]
	v_pk_add_f32 v[226:227], v[236:237], v[226:227]
	v_pk_add_f32 v[162:163], v[76:77], v[92:93]
	v_pk_add_f32 v[164:165], v[78:79], v[94:95]
	v_pk_add_f32 v[224:225], v[224:225], v[226:227]
	v_pk_add_f32 v[222:223], v[222:223], v[238:239]
	v_pk_add_f32 v[162:163], v[162:163], v[224:225]
	v_pk_add_f32 v[164:165], v[164:165], v[222:223]
	v_add_f32_e32 v162, v162, v163
	v_add_f32_e32 v163, v164, v165
	v_add_f32_e32 v162, v162, v163
	v_fmac_f32_e32 v162, v215, v170
	s_setprio 1
	v_add_u32_e32 v163, v202, v169
	ds_read_b128 v[222:225], v163 offset:52224
	ds_read_b128 v[240:243], v163 offset:56832
	ds_read_b128 v[244:247], v163 offset:61440
	ds_read_b128 v[248:251], v207 offset:52224
	v_cvt_pk_bf16_f32 v236, v64, v65
	v_cvt_pk_bf16_f32 v237, v66, v67
	v_cvt_pk_bf16_f32 v238, v68, v69
	v_cvt_pk_bf16_f32 v239, v70, v71
	s_waitcnt lgkmcnt(3)
	s_nop 0
	v_mfma_f32_32x32x16_bf16 v[48:63], v[222:225], v[236:239], v[48:63]
	ds_read_b128 v[222:225], v163 offset:52256
	s_waitcnt lgkmcnt(3)
	v_mfma_f32_32x32x16_bf16 v[32:47], v[240:243], v[236:239], v[32:47]
	ds_read_b128 v[240:243], v163 offset:56864
	s_waitcnt lgkmcnt(3)
	v_mfma_f32_32x32x16_bf16 v[16:31], v[244:247], v[236:239], v[16:31]
	ds_read_b128 v[244:247], v163 offset:61472
	s_waitcnt lgkmcnt(3)
	v_mfma_f32_32x32x16_bf16 v[0:15], v[248:251], v[236:239], v[0:15]
	ds_read_b128 v[248:251], v207 offset:52256
	v_cvt_pk_bf16_f32 v236, v72, v73
	v_cvt_pk_bf16_f32 v237, v74, v75
	v_cvt_pk_bf16_f32 v238, v76, v77
	v_cvt_pk_bf16_f32 v239, v78, v79
	s_waitcnt lgkmcnt(3)
	s_nop 0
	v_mfma_f32_32x32x16_bf16 v[48:63], v[222:225], v[236:239], v[48:63]
	ds_read_b128 v[222:225], v163 offset:52288
	s_waitcnt lgkmcnt(3)
	v_mfma_f32_32x32x16_bf16 v[32:47], v[240:243], v[236:239], v[32:47]
	ds_read_b128 v[240:243], v163 offset:56896
	s_waitcnt lgkmcnt(3)
	v_mfma_f32_32x32x16_bf16 v[16:31], v[244:247], v[236:239], v[16:31]
	ds_read_b128 v[244:247], v163 offset:61504
	s_waitcnt lgkmcnt(3)
	v_mfma_f32_32x32x16_bf16 v[0:15], v[248:251], v[236:239], v[0:15]
	ds_read_b128 v[248:251], v207 offset:52288
	v_cvt_pk_bf16_f32 v236, v80, v81
	v_cvt_pk_bf16_f32 v237, v82, v83
	v_cvt_pk_bf16_f32 v238, v84, v85
	v_cvt_pk_bf16_f32 v239, v86, v87
	s_waitcnt lgkmcnt(3)
	s_nop 0
	v_mfma_f32_32x32x16_bf16 v[48:63], v[222:225], v[236:239], v[48:63]
	ds_read_b128 v[222:225], v163 offset:52320
	s_waitcnt lgkmcnt(3)
	v_mfma_f32_32x32x16_bf16 v[32:47], v[240:243], v[236:239], v[32:47]
	ds_read_b128 v[240:243], v163 offset:56928
	s_waitcnt lgkmcnt(3)
	v_mfma_f32_32x32x16_bf16 v[16:31], v[244:247], v[236:239], v[16:31]
	ds_read_b128 v[244:247], v163 offset:61536
	s_waitcnt lgkmcnt(3)
	v_mfma_f32_32x32x16_bf16 v[0:15], v[248:251], v[236:239], v[0:15]
	ds_read_b128 v[248:251], v207 offset:52320
	v_cvt_pk_bf16_f32 v236, v88, v89
	v_cvt_pk_bf16_f32 v237, v90, v91
	v_cvt_pk_bf16_f32 v238, v92, v93
	v_cvt_pk_bf16_f32 v239, v94, v95
	s_waitcnt lgkmcnt(3)
	s_nop 0
	v_mfma_f32_32x32x16_bf16 v[48:63], v[222:225], v[236:239], v[48:63]
	s_waitcnt lgkmcnt(2)
	v_mfma_f32_32x32x16_bf16 v[32:47], v[240:243], v[236:239], v[32:47]
	s_waitcnt lgkmcnt(1)
	v_mfma_f32_32x32x16_bf16 v[16:31], v[244:247], v[236:239], v[16:31]
	s_waitcnt lgkmcnt(0)
	v_mfma_f32_32x32x16_bf16 v[0:15], v[248:251], v[236:239], v[0:15]
	s_setprio 0
	v_mov_b32_e32 v170, v234
	v_mov_b32_e32 v215, v162
.LBB0_213:
	s_or_b64 exec, exec, s[8:9]
	s_mul_i32 s8, s16, 0x4400
	v_add_u32_e32 v162, s8, v175
	s_cmp_lt_u32 s15, s12
	s_waitcnt vmcnt(3)
	ds_write_b128 v162, v[144:147]
	s_waitcnt vmcnt(2)
	ds_write_b128 v162, v[148:151] offset:8704
	s_waitcnt vmcnt(1)
	ds_write2_b64 v208, v[156:157], v[158:159] offset1:2
	v_add_u32_e32 v144, 0x2000, v208
	s_cselect_b32 s9, s15, s14
	s_waitcnt vmcnt(0)
	ds_write2_b64 v144, v[152:153], v[154:155] offset0:128 offset1:130
	s_lshl_b32 s9, s9, 6
	v_lshl_add_u64 v[152:153], s[4:5], 1, v[196:197]
	v_mad_u64_u32 v[144:145], s[10:11], s9, v228, v[194:195]
	s_or_b32 s9, s9, 32
	v_add_co_u32_e32 v154, vcc, 0x80000, v152
	v_mad_u64_u32 v[148:149], s[10:11], s9, v228, v[194:195]
	s_nop 0
	v_addc_co_u32_e32 v155, vcc, 0, v153, vcc
	s_waitcnt lgkmcnt(0)
	s_barrier
	global_load_dwordx4 v[144:147], v[144:145], off
	s_nop 0
	global_load_dwordx4 v[148:151], v[148:149], off
	s_nop 0
	global_load_dwordx4 v[156:159], v[152:153], off
	s_nop 0
	global_load_dwordx4 v[152:155], v[154:155], off
	s_add_i32 s4, s13, 34
	v_cmp_le_u32_e32 vcc, s4, v212
	s_and_b64 s[10:11], s[6:7], vcc
	s_and_saveexec_b64 s[6:7], s[10:11]
	s_cbranch_execz .LBB0_215
	s_setprio 1
	v_add3_u32 v162, v203, s8, v204
	ds_read_b128 v[80:83], v162
	ds_read_b128 v[84:87], v162 offset:32
	ds_read_b128 v[88:91], v162 offset:64
	ds_read_b128 v[92:95], v162 offset:96
	ds_read_b128 v[222:225], v162 offset:8704
	ds_read_b128 v[236:239], v162 offset:8736
	ds_read_b128 v[240:243], v162 offset:8768
	ds_read_b128 v[244:247], v162 offset:8800
	s_waitcnt lgkmcnt(7)
	v_mfma_f32_32x32x16_bf16 v[64:79], v[80:83], v[128:131], 0
	s_waitcnt lgkmcnt(6)
	v_mfma_f32_32x32x16_bf16 v[64:79], v[84:87], v[132:135], v[64:79]
	s_waitcnt lgkmcnt(5)
	v_mfma_f32_32x32x16_bf16 v[64:79], v[88:91], v[136:139], v[64:79]
	s_waitcnt lgkmcnt(4)
	v_mfma_f32_32x32x16_bf16 v[64:79], v[92:95], v[140:143], v[64:79]
	s_waitcnt lgkmcnt(3)
	v_mfma_f32_32x32x16_bf16 v[80:95], v[222:225], v[128:131], 0
	s_waitcnt lgkmcnt(2)
	v_mfma_f32_32x32x16_bf16 v[80:95], v[236:239], v[132:135], v[80:95]
	s_waitcnt lgkmcnt(1)
	v_mfma_f32_32x32x16_bf16 v[80:95], v[240:243], v[136:139], v[80:95]
	s_waitcnt lgkmcnt(0)
	v_mfma_f32_32x32x16_bf16 v[80:95], v[244:247], v[140:143], v[80:95]
	s_setprio 0
